# stick block VALU trims: 32 redundant max(x,x) canonicalisations removed, 32 per-score causal-mask index adds folded into inline-constant compares against one per-tile base
# speedup vs baseline: 1.0018x; 1.0018x over previous
; #define LAS __attribute__((address_space(3)))
; #define MFMA32(a, b, c) __builtin_amdgcn_mfma_f32_32x32x16_bf16((a), (b), (c), 0, 0, 0)
; #define EXP2(x) __builtin_amdgcn_exp2f(x)
; __device__ __forceinline__ int crow(int i, int h) { return (i & 3) + 8 * (i >> 2) + 4 * h; }
; __device__ __forceinline__ void stick_block(const bf16x8 (&qf)[4], f32x16& o0, f32x16& o1, float& carry, LAS const unsigned char* ksb, LAS const unsigned char* vtb, int r, int hh, int tq, int key0) {
;     ...
;     for (int s = 0; s < 4; ++s) { ka[s] = *(LAS const bf16x8*)(ksb + r * KSB + (16 * s + 8 * hh) * 2); kb2[s] = *(LAS const bf16x8*)(ksb + (32 + r) * KSB + (16 * s + 8 * hh) * 2); }
;     __builtin_amdgcn_s_setprio(1);
; #pragma unroll
;     for (int s = 0; s < 4; ++s) { s0 = MFMA32(ka[s], qf[s], s0); s1 = MFMA32(kb2[s], qf[s], s1); }
;     __builtin_amdgcn_s_setprio(0);
;     __builtin_amdgcn_sched_barrier(0);
;     float acc = carry;
; #pragma unroll
;     for (int kti = 0; kti < 2; ++kti) { const int kt = 1 - kti; float spm[16], G[4], R[4];
; #pragma unroll
;         for (int i = 0; i < 16; ++i) { const float z = kt ? s1[i] : s0[i]; const bool act = key0 + 32 * kt + crow(i, hh) < tq;
;             const float sp = fmaxf(z, 0.f) + __log2f(1.f + EXP2(-fabsf(z)));
;             spm[i] = act ? sp : 0.f; const float lw = act ? z - sp : -INFINITY; if (kt) s1[i] = lw; else s0[i] = lw; }
.LBB0_891:
	s_xor_b64 s[4:5], s[4:5], -1
	s_andn2_b64 vcc, exec, s[4:5]
	s_mov_b64 s[4:5], -1
	s_cbranch_vccnz .LBB0_894
	s_add_i32 s4, s17, 0xc0
	s_cmp_gt_i32 s4, s24
	s_mov_b64 s[4:5], 0
	s_cbranch_scc1 .LBB0_894
	v_add3_u32 v0, s8, v122, v92
	ds_read_b128 v[34:37], v0
	ds_read_b128 v[98:101], v0 offset:32
	ds_read_b128 v[38:41], v0 offset:4608
	ds_read_b128 v[102:105], v0 offset:4640
	ds_read_b128 v[106:109], v0 offset:64
	ds_read_b128 v[110:113], v0 offset:96
	ds_read_b128 v[190:193], v0 offset:4672
	ds_read_b128 v[194:197], v0 offset:4704
	s_setprio 1
	s_waitcnt lgkmcnt(7)
	v_mfma_f32_32x32x16_bf16 v[50:65], v[34:37], v[74:77], 0
	s_waitcnt lgkmcnt(5)
	v_mfma_f32_32x32x16_bf16 v[34:49], v[38:41], v[74:77], 0
	v_mfma_f32_32x32x16_bf16 v[50:65], v[98:101], v[78:81], v[50:65]
	s_waitcnt lgkmcnt(4)
	v_mfma_f32_32x32x16_bf16 v[34:49], v[102:105], v[78:81], v[34:49]
	s_waitcnt lgkmcnt(3)
	v_mfma_f32_32x32x16_bf16 v[50:65], v[106:109], v[82:85], v[50:65]
	s_waitcnt lgkmcnt(1)
	v_mfma_f32_32x32x16_bf16 v[34:49], v[190:193], v[82:85], v[34:49]
	v_mfma_f32_32x32x16_bf16 v[50:65], v[110:113], v[86:89], v[50:65]
	s_waitcnt lgkmcnt(0)
	v_mfma_f32_32x32x16_bf16 v[34:49], v[194:197], v[86:89], v[34:49]
	s_setprio 0
	s_nop 10
	v_exp_f32_e64 v0, -|v34|
	v_exp_f32_e64 v99, -|v35|
	v_max_f32_e32 v98, 0, v34
	v_add_f32_e32 v0, 1.0, v0
	v_log_f32_e32 v0, v0
	v_exp_f32_e64 v103, -|v37|
	s_add_i32 s99, s17, 0xd0
	v_sub_u32_e32 v121, v90, v93
	v_subrev_u32_e32 v121, s99, v121
	v_add_f32_e32 v171, v98, v0
	v_add_f32_e32 v0, 1.0, v99
	v_log_f32_e32 v0, v0
	v_max_f32_e32 v99, 0, v35
	v_add_f32_e32 v0, v99, v0
	v_exp_f32_e64 v99, -|v36|
	v_cmp_lt_i32_e64 s[4:5], 17, v121
	v_cmp_lt_i32_e64 s[42:43], 18, v121
	v_add_f32_e32 v99, 1.0, v99
	v_log_f32_e32 v99, v99
	v_add_f32_e32 v98, 1.0, v103
	v_log_f32_e32 v98, v98
	v_max_f32_e32 v102, 0, v36
	v_add_f32_e32 v165, v102, v99
	v_max_f32_e32 v102, 0, v37
	v_add_f32_e32 v167, v102, v98
	v_exp_f32_e64 v98, -|v38|
	v_exp_f32_e64 v103, -|v39|
	v_max_f32_e32 v102, 0, v38
	v_add_f32_e32 v98, 1.0, v98
	v_log_f32_e32 v98, v98
	v_exp_f32_e64 v104, -|v41|
	v_exp_f32_e64 v105, -|v45|
	v_exp_f32_e64 v107, -|v49|
	v_add_f32_e32 v169, v102, v98
	v_add_f32_e32 v98, 1.0, v103
	v_log_f32_e32 v98, v98
	v_max_f32_e32 v103, 0, v39
	v_add_f32_e32 v173, v103, v98
	v_exp_f32_e64 v98, -|v40|
	v_max_f32_e32 v103, 0, v40
	v_cmp_lt_i32_e64 s[50:51], 25, v121
	v_add_f32_e32 v98, 1.0, v98
	v_log_f32_e32 v98, v98
	v_cmp_lt_i32_e64 s[52:53], 26, v121
	v_add_f32_e32 v183, v103, v98
	v_add_f32_e32 v98, 1.0, v104
	v_log_f32_e32 v98, v98
	v_max_f32_e32 v103, 0, v41
	v_exp_f32_e64 v104, -|v43|
	v_add_f32_e32 v185, v103, v98
	v_exp_f32_e64 v98, -|v42|
	v_max_f32_e32 v103, 0, v42
	v_cmp_lt_i32_e64 s[54:55], 27, v121
	v_add_f32_e32 v98, 1.0, v98
	v_log_f32_e32 v98, v98
	v_cmp_lt_i32_e64 s[56:57], 32, v121
	v_add_f32_e32 v190, v103, v98
	v_add_f32_e32 v98, 1.0, v104
	v_log_f32_e32 v98, v98
	v_max_f32_e32 v103, 0, v43
	v_cmp_lt_i32_e64 s[58:59], 33, v121
	v_add_f32_e32 v191, v103, v98
	v_exp_f32_e64 v103, -|v44|
	v_cmp_lt_i32_e64 s[60:61], 34, v121
	v_add_f32_e32 v103, 1.0, v103
	v_log_f32_e32 v103, v103
	v_add_f32_e32 v102, 1.0, v105
	v_exp_f32_e64 v105, -|v47|
	v_max_f32_e32 v104, 0, v44
	v_add_f32_e32 v193, v104, v103
	v_cmp_lt_i32_e64 s[62:63], 35, v121
	v_cmp_lt_i32_e64 s[64:65], 40, v121
	v_add_f32_e32 v103, 1.0, v105
	v_log_f32_e32 v103, v103
	v_max_f32_e32 v105, 0, v47
	v_add_f32_e32 v147, v105, v103
	v_exp_f32_e64 v103, -|v48|
	v_max_f32_e32 v105, 0, v48
	v_add_f32_e32 v103, 1.0, v103
	v_log_f32_e32 v103, v103
	v_cmp_lt_i32_e64 s[48:49], 16, v121
	v_cmp_lt_i32_e64 s[44:45], 19, v121
	v_cndmask_b32_e64 v177, 0, v0, s[4:5]
	v_add_f32_e32 v201, v105, v103
	v_add_f32_e32 v103, 1.0, v107
	v_log_f32_e32 v103, v103
	v_cndmask_b32_e64 v101, 0, v171, s[48:49]
	v_cndmask_b32_e64 v181, 0, v165, s[42:43]
	v_cndmask_b32_e64 v187, 0, v167, s[44:45]
	v_log_f32_e32 v102, v102
	v_max_f32_e32 v105, 0, v49
	v_add_f32_e32 v203, v105, v103
	v_add_f32_e32 v101, v101, v177
	v_add_f32_e32 v103, v181, v187
	v_add_f32_e32 v110, v101, v103
	v_cmp_lt_i32_e64 s[46:47], 24, v121
	v_max_f32_e32 v104, 0, v45
	v_mov_b32_e32 v101, v110
	v_mov_b32_e32 v103, v110
	v_cndmask_b32_e64 v99, 0, v169, s[46:47]
	v_cndmask_b32_e64 v175, 0, v173, s[50:51]
	v_cndmask_b32_e64 v179, 0, v183, s[52:53]
	v_cndmask_b32_e64 v189, 0, v185, s[54:55]
	v_add_f32_e32 v140, v104, v102
	v_exp_f32_e64 v102, -|v46|
	v_permlane32_swap_b32_e32 v101, v103
	v_cndmask_b32_e64 v108, v101, v103, s[0:1]
	v_add_f32_e32 v99, v99, v175
	v_add_f32_e32 v101, v179, v189
	v_add_f32_e32 v103, v99, v101
	v_mov_b32_e32 v99, v103
	v_mov_b32_e32 v101, v103
	v_add_f32_e32 v102, 1.0, v102
	s_nop 0
	v_permlane32_swap_b32_e32 v99, v101
	v_log_f32_e32 v102, v102
	v_cndmask_b32_e64 v105, v99, v101, s[0:1]
	v_exp_f32_e64 v101, -|v50|
	v_max_f32_e32 v104, 0, v46
	v_add_f32_e32 v146, v104, v102
	v_add_f32_e32 v101, 1.0, v101
	v_cmp_lt_i32_e64 s[66:67], 41, v121
	v_log_f32_e32 v101, v101
	v_cndmask_b32_e64 v102, 0, v146, s[64:65]
	v_cndmask_b32_e64 v200, 0, v147, s[66:67]
	v_add_f32_e32 v107, v102, v200
	v_exp_f32_e64 v109, -|v53|
	v_max_f32_e32 v102, 0, v50
	v_add_f32_e32 v207, v102, v101
	v_cmp_lt_i32_e64 s[74:75], -15, v121
	v_cmp_lt_i32_e64 s[76:77], -14, v121
	v_add_f32_e32 v101, 1.0, v109
	v_log_f32_e32 v101, v101
	v_exp_f32_e64 v113, -|v55|
	v_max_f32_e32 v109, 0, v53
	v_add_f32_e32 v212, v109, v101
	v_cmp_lt_i32_e64 s[86:87], -8, v121
	v_add_f32_e32 v109, 1.0, v113
	v_log_f32_e32 v109, v109
	v_max_f32_e32 v113, 0, v55
	v_exp_f32_e64 v115, -|v57|
	v_add_f32_e32 v218, v113, v109
	v_exp_f32_e64 v109, -|v56|
	v_max_f32_e32 v113, 0, v56
; __device__ __forceinline__ float partner32(float v, int hh) { auto rr = __builtin_amdgcn_permlane32_swap(__float_as_uint(v), __float_as_uint(v), false, false); return __uint_as_float(hh ? rr[0] : rr[1]); }
; #define EXP2(x) __builtin_amdgcn_exp2f(x)
; __device__ __forceinline__ int crow(int i, int h) { return (i & 3) + 8 * (i >> 2) + 4 * h; }
; __device__ __forceinline__ void stick_block(const bf16x8 (&qf)[4], f32x16& o0, f32x16& o1, float& carry, LAS const unsigned char* ksb, LAS const unsigned char* vtb, int r, int hh, int tq, int key0) {
;     ...
;         for (int i = 0; i < 16; ++i) { const float z = kt ? s1[i] : s0[i]; const bool act = key0 + 32 * kt + crow(i, hh) < tq;
;             const float sp = fmaxf(z, 0.f) + __log2f(1.f + EXP2(-fabsf(z)));
;             spm[i] = act ? sp : 0.f; const float lw = act ? z - sp : -INFINITY; if (kt) s1[i] = lw; else s0[i] = lw; }
; #pragma unroll
;         for (int g = 0; g < 4; ++g) { G[g] = (spm[4 * g] + spm[4 * g + 1]) + (spm[4 * g + 2] + spm[4 * g + 3]); R[g] = partner32(G[g], hh); }
; #pragma unroll
;         for (int gi = 0; gi < 4; ++gi) { const int g = 3 - gi; float run = acc + (hh ? 0.f : R[g]);
; #pragma unroll
;             for (int ki = 0; ki < 4; ++ki) { const int i = 4 * g + 3 - ki; const float lw = kt ? s1[i] : s0[i]; const float wv = EXP2(lw - run); if (kt) s1[i] = wv; else s0[i] = wv; run += spm[i]; }
;             acc += G[g] + R[g]; } }
	v_add_f32_e32 v109, 1.0, v109
	v_log_f32_e32 v109, v109
	s_mov_b64 s[18:19], s[68:69]
	v_cmp_lt_i32_e64 s[68:69], 42, v121
	v_add_f32_e32 v229, v113, v109
	v_add_f32_e32 v109, 1.0, v115
	v_log_f32_e32 v109, v109
	v_max_f32_e32 v113, 0, v57
	v_exp_f32_e64 v115, -|v59|
	v_add_f32_e32 v231, v113, v109
	v_exp_f32_e64 v109, -|v58|
	v_max_f32_e32 v113, 0, v58
	s_mov_b32 s39, s38
	v_add_f32_e32 v109, 1.0, v109
	v_log_f32_e32 v109, v109
	s_mov_b32 s38, s70
	v_cmp_lt_i32_e64 s[70:71], 43, v121
	v_exp_f32_e64 v104, -|v51|
	v_add_f32_e32 v233, v113, v109
	v_add_f32_e32 v109, 1.0, v115
	v_log_f32_e32 v109, v109
	v_max_f32_e32 v113, 0, v59
	v_exp_f32_e64 v115, -|v61|
	v_add_f32_e32 v234, v113, v109
	v_exp_f32_e64 v109, -|v60|
	v_max_f32_e32 v113, 0, v60
	v_exp_f32_e64 v101, -|v54|
	v_add_f32_e32 v109, 1.0, v109
	v_log_f32_e32 v109, v109
	v_cmp_lt_i32_e64 s[72:73], -16, v121
	v_add_f32_e32 v100, 1.0, v104
	v_add_f32_e32 v236, v113, v109
	v_add_f32_e32 v109, 1.0, v115
	v_log_f32_e32 v109, v109
	v_max_f32_e32 v113, 0, v61
	v_exp_f32_e64 v115, -|v63|
	v_add_f32_e32 v238, v113, v109
	v_exp_f32_e64 v109, -|v62|
	v_max_f32_e32 v113, 0, v62
	v_log_f32_e32 v100, v100
	v_add_f32_e32 v109, 1.0, v109
	v_log_f32_e32 v109, v109
	v_add_f32_e32 v101, 1.0, v101
	v_log_f32_e32 v101, v101
	v_add_f32_e32 v240, v113, v109
	v_add_f32_e32 v109, 1.0, v115
	v_log_f32_e32 v109, v109
	v_max_f32_e32 v102, 0, v51
	v_max_f32_e32 v115, 0, v63
	v_add_f32_e32 v210, v102, v100
	v_exp_f32_e64 v102, -|v52|
	v_add_f32_e32 v241, v115, v109
	v_exp_f32_e64 v115, -|v64|
	v_max_f32_e32 v111, 0, v54
	v_add_f32_e32 v213, v111, v101
	v_exp_f32_e64 v196, -|v65|
	v_cmp_lt_i32_e64 s[80:81], -7, v121
	v_add_f32_e32 v102, 1.0, v102
	v_cmp_lt_i32_e64 s[82:83], -6, v121
	v_add_f32_e32 v115, 1.0, v115
	v_log_f32_e32 v102, v102
	v_cmp_lt_i32_e64 s[84:85], -5, v121
	v_cmp_lt_i32_e64 s[6:7], 9, v121
	v_log_f32_e32 v115, v115
	v_cmp_lt_i32_e64 s[88:89], 0, v121
	v_cmp_lt_i32_e64 s[8:9], 10, v121
	v_add_f32_e32 v113, 1.0, v196
	v_cmp_lt_i32_e64 s[90:91], 1, v121
	v_log_f32_e32 v113, v113
	v_max_f32_e32 v104, 0, v52
	v_cmp_lt_i32_e64 s[92:93], 2, v121
	v_max_f32_e32 v195, 0, v64
	v_add_f32_e32 v211, v104, v102
	v_cndmask_b32_e64 v101, 0, v213, s[86:87]
	v_cndmask_b32_e64 v219, 0, v218, s[80:81]
	v_cndmask_b32_e64 v230, 0, v229, s[82:83]
	v_cndmask_b32_e64 v232, 0, v231, s[84:85]
	v_cmp_lt_i32_e64 s[94:95], 3, v121
	v_add_f32_e32 v242, v195, v115
	v_max_f32_e32 v115, 0, v65
	v_cmp_lt_i32_e32 vcc, 11, v121
	v_add_f32_e32 v94, v101, v219
	v_add_f32_e32 v101, v230, v232
	v_add_f32_e32 v243, v115, v113
	v_add_f32_e32 v113, v94, v101
	v_mov_b32_e32 v94, v113
	v_mov_b32_e32 v101, v113
	v_cndmask_b32_e64 v194, 0, v233, s[88:89]
	v_cndmask_b32_e64 v235, 0, v234, s[90:91]
	v_cndmask_b32_e64 v237, 0, v236, s[92:93]
	v_cndmask_b32_e64 v239, 0, v238, s[94:95]
	v_permlane32_swap_b32_e32 v94, v101
	v_cndmask_b32_e64 v101, v94, v101, s[0:1]
	v_add_f32_e32 v94, v194, v235
	v_add_f32_e32 v115, v237, v239
	v_cndmask_b32_e64 v202, 0, v201, s[68:69]
	v_cndmask_b32_e64 v204, 0, v203, s[70:71]
	v_add_f32_e32 v198, v94, v115
	v_cndmask_b32_e64 v106, 0, v190, s[56:57]
	v_cndmask_b32_e64 v98, 0, v191, s[58:59]
	v_add_f32_e32 v99, v202, v204
	v_mov_b32_e32 v94, v198
	v_mov_b32_e32 v115, v198
	s_nop 1
	v_permlane32_swap_b32_e32 v94, v115
	v_pk_add_f32 v[106:107], v[106:107], v[98:99]
	v_cndmask_b32_e64 v199, v94, v115, s[0:1]
	v_mov_b32_e32 v94, v107
	v_mov_b32_e32 v99, v107
	v_cndmask_b32_e64 v192, 0, v193, s[60:61]
	v_cndmask_b32_e64 v141, 0, v140, s[62:63]
	v_permlane32_swap_b32_e32 v94, v99
	v_add_f32_e32 v114, v192, v141
	v_cndmask_b32_e64 v115, v94, v99, s[0:1]
	v_pk_add_f32 v[106:107], v[106:107], v[114:115]
	v_cmp_lt_i32_e64 s[96:97], 8, v121
	v_mov_b32_e32 v94, v106
	v_mov_b32_e32 v99, v106
	s_nop 1
	v_permlane32_swap_b32_e32 v94, v99
	v_cndmask_b32_e64 v94, v94, v99, s[0:1]
	v_pk_add_f32 v[106:107], v[106:107], v[94:95]
	v_cndmask_b32_e32 v244, 0, v243, vcc
	v_cndmask_b32_e64 v99, 0, v115, s[0:1]
	v_pk_add_f32 v[114:115], v[106:107], v[106:107] op_sel:[0,1] op_sel_hi:[1,0]
	v_cndmask_b32_e64 v111, 0, v240, s[96:97]
	v_cndmask_b32_e64 v109, 0, v241, s[6:7]
	v_cndmask_b32_e64 v195, 0, v242, s[8:9]
	v_add_f32_e32 v194, v103, v105
	v_mov_b32_e32 v115, v244
	v_pk_add_f32 v[196:197], v[194:195], v[114:115]
	v_pk_add_f32 v[110:111], v[110:111], v[108:109]
	v_cndmask_b32_e64 v247, 0, v94, s[0:1]
	v_pk_add_f32 v[110:111], v[110:111], v[196:197]
	v_cmp_lt_i32_e64 s[78:79], -13, v121
	v_mov_b32_e32 v94, v111
	v_mov_b32_e32 v103, v111
	s_nop 1
	v_permlane32_swap_b32_e32 v94, v103
	v_cndmask_b32_e64 v94, v94, v103, s[0:1]
	v_cndmask_b32_e64 v106, 0, v94, s[0:1]
	v_add_f32_e32 v94, v111, v94
	v_cndmask_b32_e64 v205, 0, v105, s[0:1]
	v_cndmask_b32_e64 v102, 0, v211, s[76:77]
	v_cndmask_b32_e64 v104, 0, v212, s[78:79]
	v_cndmask_b32_e64 v245, 0, v199, s[0:1]
	v_add_f32_e32 v105, v110, v94
	v_add_f32_e32 v103, v198, v199
	v_sub_f32_e32 v61, v61, v238
	v_pk_add_f32 v[198:199], v[102:103], v[104:105]
	v_sub_f32_e32 v65, v65, v243
	v_cndmask_b32_e64 v61, v215, v61, s[94:95]
	v_add_f32_e32 v105, v245, v105
	v_sub_f32_e32 v60, v60, v236
	v_cndmask_b32_e64 v246, 0, v101, s[0:1]
	v_cndmask_b32_e32 v65, v215, v65, vcc
	v_add_f32_e32 v106, v110, v106
	v_sub_f32_e32 v64, v64, v242
	v_sub_f32_e32 v61, v61, v105
	v_cndmask_b32_e64 v60, v215, v60, s[92:93]
	v_add_f32_e32 v105, v239, v105
	v_sub_f32_e32 v59, v59, v234
	v_sub_f32_e32 v57, v57, v231
	v_cndmask_b32_e64 v206, 0, v108, s[0:1]
	v_add_f32_e32 v103, v246, v199
	v_sub_f32_e32 v65, v65, v106
	v_cndmask_b32_e64 v64, v215, v64, s[8:9]
	v_add_f32_e32 v106, v244, v106
	v_sub_f32_e32 v63, v63, v241
; #define LAS __attribute__((address_space(3)))
; __device__ __forceinline__ unsigned cvtpk(float lo, float hi) { f32x2_t v = {lo, hi}; bf16x2_t b = __builtin_convertvector(v, bf16x2_t); return __builtin_bit_cast(unsigned, b); }
; #define EXP2(x) __builtin_amdgcn_exp2f(x)
; __device__ __forceinline__ void pv_accum(const f32x16& s0, const f32x16& s1, f32x16& o0, f32x16& o1, LAS const unsigned char* vtb, int r, int hh) {
;     __builtin_amdgcn_s_setprio(1);
; #pragma unroll
;     for (int kt = 0; kt < 2; ++kt)
; #pragma unroll
;         for (int sp = 0; sp < 2; ++sp) { u32x4 w;
;             if (kt == 0) { w.x = cvtpk(s0[8 * sp], s0[8 * sp + 1]); w.y = cvtpk(s0[8 * sp + 2], s0[8 * sp + 3]); w.z = cvtpk(s0[8 * sp + 4], s0[8 * sp + 5]); w.w = cvtpk(s0[8 * sp + 6], s0[8 * sp + 7]); }
;             else         { w.x = cvtpk(s1[8 * sp], s1[8 * sp + 1]); w.y = cvtpk(s1[8 * sp + 2], s1[8 * sp + 3]); w.z = cvtpk(s1[8 * sp + 4], s1[8 * sp + 5]); w.w = cvtpk(s1[8 * sp + 6], s1[8 * sp + 7]); }
;             const bf16x8 pb = __builtin_bit_cast(bf16x8, w); const int ko = 32 * kt + 16 * sp + 4 * hh;
;             { const s16x4 lo = *(LAS const s16x4*)(vtb + r * VTB + ko * 2), hi = *(LAS const s16x4*)(vtb + r * VTB + (ko + 8) * 2);
; __device__ __forceinline__ void stick_block(const bf16x8 (&qf)[4], f32x16& o0, f32x16& o1, float& carry, LAS const unsigned char* ksb, LAS const unsigned char* vtb, int r, int hh, int tq, int key0) {
;     ...
;         for (int gi = 0; gi < 4; ++gi) { const int g = 3 - gi; float run = acc + (hh ? 0.f : R[g]);
; #pragma unroll
;             for (int ki = 0; ki < 4; ++ki) { const int i = 4 * g + 3 - ki; const float lw = kt ? s1[i] : s0[i]; const float wv = EXP2(lw - run); if (kt) s1[i] = wv; else s0[i] = wv; run += spm[i]; }
;             acc += G[g] + R[g]; } }
;     carry = acc;
;     __builtin_amdgcn_sched_barrier(0);
;     pv_accum(s0, s1, o0, o1, vtb, r, hh);
	v_sub_f32_e32 v60, v60, v105
	v_cndmask_b32_e64 v59, v215, v59, s[90:91]
	v_add_f32_e32 v105, v237, v105
	v_sub_f32_e32 v58, v58, v233
	v_cndmask_b32_e64 v57, v215, v57, s[84:85]
	v_add_f32_e32 v108, v232, v103
	v_sub_f32_e32 v64, v64, v106
	v_cndmask_b32_e64 v63, v215, v63, s[6:7]
	v_add_f32_e32 v106, v195, v106
	v_sub_f32_e32 v62, v62, v240
	v_sub_f32_e32 v59, v59, v105
	v_cndmask_b32_e64 v58, v215, v58, s[88:89]
	v_add_f32_e32 v105, v235, v105
	v_sub_f32_e32 v57, v57, v103
	v_add_f32_e32 v103, v206, v196
	v_sub_f32_e32 v63, v63, v106
	v_cndmask_b32_e64 v62, v215, v62, s[96:97]
	v_add_f32_e32 v106, v109, v106
	v_sub_f32_e32 v58, v58, v105
	v_sub_f32_e32 v56, v56, v229
	v_add_f32_e32 v105, v187, v103
	v_sub_f32_e32 v62, v62, v106
	v_cndmask_b32_e64 v56, v215, v56, s[82:83]
	v_sub_f32_e32 v34, v34, v171
	v_add_f32_e32 v106, v181, v105
	v_add_f32_e32 v111, v230, v108
	v_sub_f32_e32 v56, v56, v108
	v_cndmask_b32_e64 v34, v215, v34, s[48:49]
	v_add_f32_e32 v108, v177, v106
	v_sub_f32_e32 v34, v34, v108
	v_exp_f32_e32 v108, v34
	v_sub_f32_e32 v34, v49, v203
	v_cndmask_b32_e64 v34, v215, v34, s[70:71]
	v_add_f32_e32 v49, v95, v99
	v_sub_f32_e32 v34, v34, v49
	v_exp_f32_e32 v99, v34
	v_sub_f32_e32 v34, v48, v201
	v_cndmask_b32_e64 v34, v215, v34, s[68:69]
	v_add_f32_e32 v48, v204, v49
	v_sub_f32_e32 v34, v34, v48
	v_exp_f32_e32 v49, v34
	v_sub_f32_e32 v34, v47, v147
	v_cndmask_b32_e64 v34, v215, v34, s[66:67]
	v_add_f32_e32 v47, v202, v48
	v_sub_f32_e32 v34, v34, v47
	v_exp_f32_e32 v48, v34
	v_sub_f32_e32 v34, v46, v146
	v_cndmask_b32_e64 v34, v215, v34, s[64:65]
	v_add_f32_e32 v46, v200, v47
	v_sub_f32_e32 v34, v34, v46
	v_exp_f32_e32 v46, v34
	v_sub_f32_e32 v34, v45, v140
	v_cndmask_b32_e64 v34, v215, v34, s[62:63]
	v_add_f32_e32 v45, v247, v107
	v_sub_f32_e32 v34, v34, v45
	v_exp_f32_e32 v47, v34
	v_sub_f32_e32 v34, v44, v193
	v_cndmask_b32_e64 v34, v215, v34, s[60:61]
	v_add_f32_e32 v44, v141, v45
	v_sub_f32_e32 v34, v34, v44
	v_exp_f32_e32 v45, v34
	v_sub_f32_e32 v34, v43, v191
	v_cndmask_b32_e64 v34, v215, v34, s[58:59]
	v_add_f32_e32 v43, v192, v44
	v_sub_f32_e32 v34, v34, v43
	v_exp_f32_e32 v44, v34
	v_sub_f32_e32 v34, v42, v190
	v_add_u32_e32 v117, s37, v123
	ds_read_b64_tr_b16 v[190:191], v117 offset:36864
	ds_read_b64_tr_b16 v[192:193], v117 offset:38400
	ds_read_b64_tr_b16 v[194:195], v117 offset:36928
	ds_read_b64_tr_b16 v[196:197], v117 offset:38464
	ds_read_b64_tr_b16 v[200:201], v117 offset:39936
	ds_read_b64_tr_b16 v[202:203], v117 offset:41472
	ds_read_b64_tr_b16 v[230:231], v117 offset:40000
	ds_read_b64_tr_b16 v[232:233], v117 offset:41536
	ds_read_b64_tr_b16 v[234:235], v117 offset:43008
	ds_read_b64_tr_b16 v[236:237], v117 offset:44544
	ds_read_b64_tr_b16 v[238:239], v117 offset:43072
	ds_read_b64_tr_b16 v[240:241], v117 offset:44608
	ds_read_b64_tr_b16 v[242:243], v117 offset:46080
	ds_read_b64_tr_b16 v[244:245], v117 offset:47616
	v_cndmask_b32_e64 v34, v215, v34, s[56:57]
	v_add_f32_e32 v42, v98, v43
	v_sub_f32_e32 v34, v34, v42
	v_exp_f32_e32 v42, v34
	v_sub_f32_e32 v34, v41, v185
	v_cndmask_b32_e64 v34, v215, v34, s[54:55]
	v_add_f32_e32 v41, v205, v114
	v_sub_f32_e32 v34, v34, v41
	v_exp_f32_e32 v43, v34
	v_sub_f32_e32 v34, v40, v183
	v_cndmask_b32_e64 v34, v215, v34, s[52:53]
	v_add_f32_e32 v40, v189, v41
	v_sub_f32_e32 v34, v34, v40
	v_exp_f32_e32 v98, v34
	v_sub_f32_e32 v34, v39, v173
	v_cndmask_b32_e64 v34, v215, v34, s[50:51]
	v_add_f32_e32 v39, v179, v40
	v_sub_f32_e32 v34, v34, v39
	v_exp_f32_e32 v107, v34
	v_sub_f32_e32 v34, v38, v169
	v_cndmask_b32_e64 v34, v215, v34, s[46:47]
	v_add_f32_e32 v38, v175, v39
	v_cndmask_b32_e64 v112, 0, v207, s[72:73]
	v_cndmask_b32_e64 v100, 0, v210, s[74:75]
	v_sub_f32_e32 v34, v34, v38
	v_pk_add_f32 v[112:113], v[112:113], v[100:101]
	v_exp_f32_e32 v109, v34
	v_sub_f32_e32 v34, v37, v167
	v_pk_add_f32 v[112:113], v[112:113], v[198:199]
	v_cndmask_b32_e64 v34, v215, v34, s[44:45]
	v_mov_b32_e32 v94, v112
	v_mov_b32_e32 v101, v112
	v_sub_f32_e32 v34, v34, v103
	s_nop 0
	v_permlane32_swap_b32_e32 v94, v101
	v_exp_f32_e32 v103, v34
	v_sub_f32_e32 v34, v36, v165
	v_cndmask_b32_e64 v94, v94, v101, s[0:1]
	v_cndmask_b32_e64 v34, v215, v34, s[42:43]
	v_cndmask_b32_e64 v101, 0, v94, s[0:1]
	v_sub_f32_e32 v53, v53, v212
	v_sub_f32_e32 v34, v34, v105
	v_sub_f32_e32 v52, v52, v211
	v_cndmask_b32_e64 v53, v215, v53, s[78:79]
	v_exp_f32_e32 v105, v34
	v_add_f32_e32 v34, v101, v113
	v_sub_f32_e32 v51, v51, v210
	v_cndmask_b32_e64 v52, v215, v52, s[76:77]
	v_sub_f32_e32 v0, v35, v0
	v_sub_f32_e32 v35, v53, v34
	v_add_f32_e32 v34, v104, v34
	v_sub_f32_e32 v50, v50, v207
	v_cndmask_b32_e64 v51, v215, v51, s[74:75]
	v_exp_f32_e32 v39, v35
	v_sub_f32_e32 v35, v52, v34
	v_add_f32_e32 v34, v102, v34
	v_cndmask_b32_e64 v50, v215, v50, s[72:73]
	v_exp_f32_e32 v40, v35
	v_sub_f32_e32 v35, v51, v34
	v_add_f32_e32 v34, v100, v34
	v_sub_f32_e32 v54, v54, v213
	v_sub_f32_e32 v55, v55, v218
	v_sub_f32_e32 v34, v50, v34
	v_cndmask_b32_e64 v54, v215, v54, s[86:87]
	v_add_f32_e32 v115, v219, v111
	v_cndmask_b32_e64 v55, v215, v55, s[80:81]
	v_cndmask_b32_e64 v0, v215, v0, s[4:5]
	v_exp_f32_e32 v41, v34
	v_add_f32_e32 v34, v112, v94
	v_sub_f32_e32 v54, v54, v115
	v_sub_f32_e32 v55, v55, v111
	s_mov_b32 s73, 0xc2ce8ed0
	s_movk_i32 s72, 0x1000
	s_brev_b32 s75, -2
	s_mov_b32 s74, 0x42b17218
	s_mov_b32 s71, 0x800000
	s_mov_b32 s70, s38
	s_mov_b32 s38, s39
	s_movk_i32 s39, 0x1800
	s_mov_b64 s[68:69], s[18:19]
	v_readlane_b32 s67, v252, 8
	v_sub_f32_e32 v0, v0, v106
	v_add_f32_e32 v95, v34, v113
	v_exp_f32_e32 v54, v54
	v_exp_f32_e32 v65, v65
	v_exp_f32_e32 v64, v64
	v_exp_f32_e32 v63, v63
	v_exp_f32_e32 v62, v62
	v_exp_f32_e32 v61, v61
	v_exp_f32_e32 v60, v60
	v_exp_f32_e32 v59, v59
	v_exp_f32_e32 v58, v58
	v_exp_f32_e32 v57, v57
	v_exp_f32_e32 v56, v56
	v_exp_f32_e32 v55, v55
	v_exp_f32_e32 v0, v0
	v_exp_f32_e32 v38, v35
	s_setprio 1
	ds_read_b64_tr_b16 v[34:35], v117 offset:46144
	ds_read_b64_tr_b16 v[36:37], v117 offset:47680
	v_cvt_pk_bf16_f32 v38, v41, v38
	v_cvt_pk_bf16_f32 v39, v40, v39
	v_cvt_pk_bf16_f32 v40, v54, v55
	v_cvt_pk_bf16_f32 v41, v56, v57
	s_waitcnt lgkmcnt(2)
; #define LAS __attribute__((address_space(3)))
; __device__ __forceinline__ unsigned cvtpk(float lo, float hi) { f32x2_t v = {lo, hi}; bf16x2_t b = __builtin_convertvector(v, bf16x2_t); return __builtin_bit_cast(unsigned, b); }
; #define MFMA32(a, b, c) __builtin_amdgcn_mfma_f32_32x32x16_bf16((a), (b), (c), 0, 0, 0)
; __device__ __forceinline__ void pv_accum(const f32x16& s0, const f32x16& s1, f32x16& o0, f32x16& o1, LAS const unsigned char* vtb, int r, int hh) {
;     __builtin_amdgcn_s_setprio(1);
; #pragma unroll
;     for (int kt = 0; kt < 2; ++kt)
; #pragma unroll
;         for (int sp = 0; sp < 2; ++sp) { u32x4 w;
;             if (kt == 0) { w.x = cvtpk(s0[8 * sp], s0[8 * sp + 1]); w.y = cvtpk(s0[8 * sp + 2], s0[8 * sp + 3]); w.z = cvtpk(s0[8 * sp + 4], s0[8 * sp + 5]); w.w = cvtpk(s0[8 * sp + 6], s0[8 * sp + 7]); }
;             else         { w.x = cvtpk(s1[8 * sp], s1[8 * sp + 1]); w.y = cvtpk(s1[8 * sp + 2], s1[8 * sp + 3]); w.z = cvtpk(s1[8 * sp + 4], s1[8 * sp + 5]); w.w = cvtpk(s1[8 * sp + 6], s1[8 * sp + 7]); }
;             const bf16x8 pb = __builtin_bit_cast(bf16x8, w); const int ko = 32 * kt + 16 * sp + 4 * hh;
;             { const s16x4 lo = *(LAS const s16x4*)(vtb + r * VTB + ko * 2), hi = *(LAS const s16x4*)(vtb + r * VTB + (ko + 8) * 2);
;               o0 = MFMA32(__builtin_shufflevector(lo, hi, 0, 1, 2, 3, 4, 5, 6, 7), pb, o0); }
;             { const s16x4 lo = *(LAS const s16x4*)(vtb + (32 + r) * VTB + ko * 2), hi = *(LAS const s16x4*)(vtb + (32 + r) * VTB + (ko + 8) * 2);
;               o1 = MFMA32(__builtin_shufflevector(lo, hi, 0, 1, 2, 3, 4, 5, 6, 7), pb, o1); } }
;     __builtin_amdgcn_s_setprio(0);
; __device__ __forceinline__ void stick_item(const StickArgs& A, int item, LAS unsigned char* lds, int tid) {
;     ...
;         { if (!done && 64 * id <= T0 + 32 * w + 30) { stick_block(qf, o0, o1, carry, ksb, vtb, r, hh, tq, 64 * id); done = __all(carry > 150.1f); }
	s_nop 0
	v_mfma_f32_32x32x16_bf16 v[18:33], v[190:193], v[38:41], v[18:33]
	v_mfma_f32_32x32x16_bf16 v[2:17], v[194:197], v[38:41], v[2:17]
	s_nop 0
	v_cvt_pk_bf16_f32 v38, v58, v59
	v_cvt_pk_bf16_f32 v39, v60, v61
	v_cvt_pk_bf16_f32 v40, v62, v63
	v_cvt_pk_bf16_f32 v41, v64, v65
	s_nop 1
	v_mfma_f32_32x32x16_bf16 v[18:33], v[200:203], v[38:41], v[18:33]
	v_mfma_f32_32x32x16_bf16 v[2:17], v[230:233], v[38:41], v[2:17]
	s_nop 0
	v_cvt_pk_bf16_f32 v38, v108, v0
	v_cvt_pk_bf16_f32 v39, v105, v103
	v_cvt_pk_bf16_f32 v40, v109, v107
	v_cvt_pk_bf16_f32 v41, v98, v43
	s_nop 1
	v_mfma_f32_32x32x16_bf16 v[18:33], v[234:237], v[38:41], v[18:33]
	v_mfma_f32_32x32x16_bf16 v[2:17], v[238:241], v[38:41], v[2:17]
	s_nop 0
	v_cvt_pk_bf16_f32 v38, v42, v44
	v_cvt_pk_bf16_f32 v39, v45, v47
	v_cvt_pk_bf16_f32 v40, v46, v48
	v_cvt_pk_bf16_f32 v41, v49, v99
	s_waitcnt lgkmcnt(0)
	s_nop 0
	v_mfma_f32_32x32x16_bf16 v[18:33], v[242:245], v[38:41], v[18:33]
	v_mfma_f32_32x32x16_bf16 v[2:17], v[34:37], v[38:41], v[2:17]
	s_setprio 0
	s_mov_b32 s4, 0x4316199a
	v_cmp_lt_f32_e32 vcc, s4, v95
	s_cmp_eq_u64 vcc, exec
	s_cselect_b64 s[4:5], -1, 0
